# same as previous + dead s_nop padding so the six GEMM K-loop heads keep the baseline's address mod 64
# baseline (speedup 1.0000x reference)
.LBB0_84:
	s_cmp_lt_i32 s82, 2
	s_cselect_b64 s[0:1], -1, 0
	s_and_b64 s[0:1], s[0:1], s[2:3]
	s_andn2_b64 vcc, exec, s[0:1]
	s_cbranch_vccnz .LBB0_105
	s_mov_b64 s[2:3], 0
	v_readlane_b32 s26, v254, 0
	v_mov_b32_e32 v0, v230
	v_mov_b32_e32 v8, v230
	s_cmpk_gt_i32 s26, 0x7f
	v_readfirstlane_b32 s27, v8
	s_cbranch_scc1 .LBB0_105
	s_ashr_i32 s28, s26, 31
	s_lshr_b32 s4, s28, 29
	s_add_i32 s8, s26, s4
	s_and_b32 s4, s8, -8
	s_sub_i32 s6, s26, s4
	s_cmp_gt_i32 s6, -1
	s_cbranch_scc0 .LBB0_88
	s_lshl_b32 s7, s6, 4
	s_ashr_i32 s4, s8, 3
	s_cbranch_execz .LBB0_89
	s_branch .LBB0_90
	s_nop 0
	s_nop 0
	s_nop 0
	s_nop 0
	s_nop 0
	s_nop 0
	s_nop 0
	s_nop 0

.LBB0_519:
	s_lshl_b32 s0, s28, 26
	s_add_u32 s0, s18, s0
	s_addc_u32 s1, s19, 0
	s_add_u32 s0, s0, 0x3c00000
	v_lshrrev_b32_e32 v17, 1, v13
	s_addc_u32 s1, s1, 0
	v_and_b32_e32 v17, 24, v17
	s_add_u32 s40, s18, 0x19c00000
	v_and_b32_e32 v16, 15, v13
	v_lshlrev_b32_e32 v18, 1, v17
	v_lshlrev_b32_e32 v13, 2, v13
	s_addc_u32 s41, s19, 0
	s_and_b32 s6, s20, 3
	v_lshl_or_b32 v179, s21, 6, v16
	v_lshl_or_b32 v16, v16, 6, v18
	s_lshl_b32 s7, s21, 13
	v_and_b32_e32 v13, 32, v13
	v_bitop3_b32 v18, v16, s7, v13 bitop3:0xde
	s_lshl_b32 s7, s6, 12
	s_add_i32 m0, s3, 0x18000
	v_lshl_add_u64 v[8:9], v[8:9], 0, s[24:25]
	v_bitop3_b32 v184, v16, s7, v13 bitop3:0xde
	s_waitcnt vmcnt(4)
	s_barrier
	global_load_lds_dwordx4 v[8:9], off
	v_lshl_add_u64 v[6:7], v[6:7], 0, s[24:25]
	s_add_i32 m0, s3, 0x1a000
	s_add_i32 s7, s3, 0x8000
	s_add_i32 s18, s3, 0xa000
	global_load_lds_dwordx4 v[6:7], off
	v_lshl_add_u64 v[4:5], v[4:5], 0, s[24:25]
	s_mov_b32 m0, s7
	s_add_u32 s20, s90, 0x20080
	global_load_lds_dwordx4 v[4:5], off
	v_lshl_add_u64 v[2:3], v[2:3], 0, s[24:25]
	s_mov_b32 m0, s18
	s_addc_u32 s21, s91, 0
	global_load_lds_dwordx4 v[2:3], off
	s_add_i32 m0, s3, 0x1c000
	v_lshl_add_u64 v[2:3], s[20:21], 0, v[162:163]
	global_load_lds_dwordx4 v[2:3], off
	v_lshl_add_u64 v[2:3], s[20:21], 0, v[164:165]
	s_add_i32 m0, s3, 0x1e000
	v_or_b32_e32 v186, 16, v179
	global_load_lds_dwordx4 v[2:3], off
	v_lshlrev_b32_e32 v2, 8, v179
	v_and_b32_e32 v185, 0xcf00, v2
	v_lshlrev_b32_e32 v2, 8, v186
	v_or_b32_e32 v188, 32, v179
	v_and_b32_e32 v187, 0xdf00, v2
	v_lshlrev_b32_e32 v2, 8, v188
	v_or_b32_e32 v190, 48, v179
	v_and_b32_e32 v189, 0xef00, v2
	v_lshlrev_b32_e32 v2, 8, v190
	v_add_u32_e32 v192, 0x80, v179
	v_and_b32_e32 v191, 0xff00, v2
	v_lshlrev_b32_e32 v2, 8, v192
	v_add_u32_e32 v194, 0x90, v179
	v_and_b32_e32 v193, 0xcf00, v2
	v_lshlrev_b32_e32 v2, 8, v194
	v_add_u32_e32 v196, 0xa0, v179
	v_and_b32_e32 v195, 0xdf00, v2
	v_lshlrev_b32_e32 v2, 8, v196
	v_add_u32_e32 v198, 0xb0, v179
	v_and_b32_e32 v197, 0xef00, v2
	v_lshlrev_b32_e32 v2, 8, v198
	v_and_b32_e32 v199, 0xff00, v2
	v_lshlrev_b32_e32 v2, 13, v0
	v_and_b32_e32 v2, 0xffffc000, v2
	v_lshl_add_u32 v2, v10, 10, v2
	v_and_b32_e32 v0, 1, v0
	v_lshl_or_b32 v0, v0, 6, v2
	v_lshl_add_u32 v166, v11, 1, v0
	v_lshlrev_b32_e32 v0, 13, v12
	v_and_b32_e32 v0, 0xffffc000, v0
	s_waitcnt vmcnt(6)
	v_lshl_add_u32 v0, v14, 10, v0
	v_and_b32_e32 v2, 1, v12
	v_lshl_or_b32 v0, v2, 6, v0
	s_ashr_i32 s19, s8, 31
	v_lshl_or_b32 v200, s6, 6, v17
	v_mov_b32_e32 v167, v1
	v_lshl_add_u32 v168, v15, 1, v0
	v_mov_b32_e32 v169, v1
	s_mov_b32 s20, 0
	v_add_u32_e32 v201, 0, v18
	s_barrier
	s_branch .LBB0_521
	s_nop 0
	s_nop 0
	s_nop 0
	s_nop 0
	s_nop 0
	s_nop 0
	s_nop 0
	s_nop 0
	s_nop 0
	s_nop 0
	s_nop 0
	s_nop 0
